# v207 with the last grid barrier's code warm-up limited to 12 KB (stays inside .text)
# speedup vs baseline: 1.0026x; 1.0026x over previous
.LBB0_686:
	s_or_b64 exec, exec, s[0:1]
	v_readfirstlane_b32 s4, v0
	s_lshr_b32 s4, s4, 6
	s_cmp_lg_u32 s4, 2
	s_cbranch_scc1 .Lmy_nopf_9
	s_sleep 60
	s_getpc_b64 s[4:5]
	v_and_b32_e32 v2, 63, v0
	v_lshlrev_b32_e32 v2, 4, v2
	global_load_dwordx4 v[4:7], v2, s[4:5]
	global_load_dwordx4 v[4:7], v2, s[4:5] offset:1024
	global_load_dwordx4 v[4:7], v2, s[4:5] offset:2048
	global_load_dwordx4 v[4:7], v2, s[4:5] offset:3072
	s_add_u32 s4, s4, 0x1000
	s_addc_u32 s5, s5, 0
	global_load_dwordx4 v[4:7], v2, s[4:5]
	global_load_dwordx4 v[4:7], v2, s[4:5] offset:1024
	global_load_dwordx4 v[4:7], v2, s[4:5] offset:2048
	global_load_dwordx4 v[4:7], v2, s[4:5] offset:3072
	s_add_u32 s4, s4, 0x1000
	s_addc_u32 s5, s5, 0
	global_load_dwordx4 v[4:7], v2, s[4:5]
	global_load_dwordx4 v[4:7], v2, s[4:5] offset:1024
	global_load_dwordx4 v[4:7], v2, s[4:5] offset:2048
	global_load_dwordx4 v[4:7], v2, s[4:5] offset:3072
	s_waitcnt vmcnt(0)
